# P5 epilogue pipelined; P8: workgroups with bit 3 of their id set run their K-slice unit first, so the residual-epilogue bursts of the two halves interleave
# speedup vs baseline: 1.0073x; 1.0017x over previous
;     __host__ __device__ __forceinline__ bool next(int i, Unit& u) const {
;         const long L = (long)i * G + c; if (L >= nwg + 32 * NSPLIT) return false;
;         Unit a; map(L < nwg ? (int)L : 0, a);
;         const bool sp = L >= nwg; const int j = sp ? (int)L - nwg : 0, tile = j / NSPLIT, ks = j % NSPLIT, base = nch / NSPLIT, rem = nch % NSPLIT;
;         u.pm = sp ? 64 + (tile >> 3) : a.pm; u.pn = sp ? (tile & 7) : a.pn; u.ks = sp ? ks : -1;
;         u.k0 = sp ? (ks * base + (ks < rem ? ks : rem)) * 128 : 0; u.nt = sp ? (base + (ks < rem ? 1 : 0)) * 2 : ntk; return true;
.LBB0_1168:
	s_or_b64 exec, exec, s[4:5]
	s_mov_b64 s[22:23], s[0:1]
	s_waitcnt lgkmcnt(0)
	v_mov_b32_e32 v0, v254
	s_barrier
	s_mov_b32 s99, 0
	s_load_dwordx2 s[6:7], s[22:23], 0xb0
	v_mov_b32_e32 v8, v254
	v_cndmask_b32_e64 v0, 0, 1, s[18:19]
	v_cmp_ne_u32_e64 s[4:5], 1, v0
	s_andn2_b64 vcc, exec, s[18:19]
	v_readfirstlane_b32 s28, v8
	s_cbranch_vccnz .LBB0_1171
	s_bitcmp1_b32 s2, 3
	s_cselect_b32 s99, 0x200, 0
	s_cmpk_eq_u32 s48, 0x100
	s_cselect_b32 s99, s99, 0
	s_add_i32 s2, s2, s99
	s_cmpk_gt_i32 s2, 0x1ff
	s_cselect_b64 s[8:9], -1, 0
	s_ashr_i32 s3, s2, 31
	s_lshr_b32 s3, s3, 29
	s_add_i32 s3, s2, s3
	s_and_b32 s10, s3, -8
	s_sub_i32 s10, s2, s10
	s_cmpk_lt_i32 s2, 0x200
	s_cselect_b32 s18, s10, 0
	s_cmp_gt_i32 s18, -1
	s_cbranch_scc0 .LBB0_1172
	s_lshl_b32 s13, s18, 6
	s_cbranch_execz .LBB0_1173
	s_branch .LBB0_1174

;     __host__ __device__ void init(int G_, int c_, int K) { StaticOrder::init(64 * BM, 2048, G_, c_, K); nch = K / 128; }
; #define PG8_STAGE(bufoff, gbase, voff) do { _Pragma("unroll") for (int _i = 0; _i < 2; ++_i) \
;         __builtin_amdgcn_global_load_lds((const unsigned*)((const char*)(gbase) + (voff)[_i]), (PG8_LAS unsigned*)(lds + (bufoff) + ldsw + _i * 8192), 16, 0, 0); } while (0)
; #define PG8_WAIT_V(n) asm volatile("s_waitcnt vmcnt(" #n ")" ::: "memory")
; #define PG8_BAR __builtin_amdgcn_s_barrier()
; template <class Epi, class Sched, bool ALIGN_EPI = false, bool SP2 = false>
; __device__ __forceinline__ void gemm_phase(PG8_LAS unsigned char* lds, const Gemm g, const Sched& S, const Epi& E) {
;     ...
;         PG8_STAGE(PG8_SB(0, 0), cB, voffB); PG8_STAGE(PG8_SB(0, 1), cB + hstepB, voffB); PG8_STAGE(PG8_SA(0, 0), cA, voffA); PG8_STAGE(PG8_SA(0, 1), cA + hstepA, voffA);
;         if (wr == 1) PG8_BAR;
;         PG8_WAIT_V(2); PG8_BAR;
;         PG8_STAGE(PG8_SB(1, 0), cB + kstep, voffB); PG8_STAGE(PG8_SA(1, 0), cA + kstep, voffA); PG8_STAGE(PG8_SB(1, 1), cB + hstepB + kstep, voffB);
;         PG8_WAIT_V(6); PG8_BAR;
; __global__ void __launch_bounds__(512, 2) fwd_kernel(Params P) {
;     ...
;         pg8::Gemm g{Hb, WdT, DFF, DFF, DFF, 0, nullptr, 0}; pg8::SplitOrder S; S.init(G, bx, DFF);
;         EpiRes<true> E{(const bf16*)(ws + WS_R1), mod + 5 * DM, (bf16*)(ws + WS_R1), (float*)(ws + WS_PART8), (const float*)(ws + WS_STATS), ln1g, ln1b};
;         pg8::gemm_phase<EpiRes<true>, pg8::SplitOrder, true, true>(lds, g, S, E);
.LBB0_1181:
	s_add_u32 s22, s6, 0x1c500000
	s_addc_u32 s23, s7, 0
	s_add_u32 s60, s6, 0x6f0a000
	s_addc_u32 s61, s7, 0
	s_add_u32 s62, s6, 0x7000000
	s_addc_u32 s63, s7, 0
	s_add_u32 s24, s6, 0x20900000
	s_addc_u32 s25, s7, 0
	s_lshl_b32 s6, s26, 5
	s_mov_b64 s[26:27], 0x80
	s_and_b32 s34, s6, 0x60
	s_add_i32 m0, s56, 0x18000
	v_lshl_add_u64 v[6:7], v[6:7], 0, s[26:27]
	s_lshl_b32 s29, s4, 13
	s_lshl_b32 s35, s34, 7
	s_waitcnt vmcnt(2)
	s_barrier
	global_load_lds_dwordx4 v[6:7], off
	v_lshl_add_u64 v[2:3], v[2:3], 0, s[26:27]
	s_add_i32 m0, s56, 0x1a000
	s_add_i32 s64, s56, 0x8000
	s_add_i32 s65, s56, 0xa000
	global_load_lds_dwordx4 v[2:3], off
	v_lshl_add_u64 v[0:1], v[0:1], 0, s[26:27]
	s_mov_b32 m0, s64
	s_add_u32 s6, s50, 0x160080
	global_load_lds_dwordx4 v[0:1], off
	v_lshl_add_u64 v[0:1], v[4:5], 0, s[26:27]
	s_mov_b32 m0, s65
	s_addc_u32 s7, s51, 0
	global_load_lds_dwordx4 v[0:1], off
	s_add_i32 m0, s56, 0x1c000
	v_lshl_add_u64 v[0:1], s[6:7], 0, v[162:163]
	global_load_lds_dwordx4 v[0:1], off
	v_lshl_add_u64 v[0:1], s[6:7], 0, v[166:167]
	s_add_i32 m0, s56, 0x1e000
	s_mov_b64 s[6:7], 0x160080
	global_load_lds_dwordx4 v[0:1], off
	v_lshrrev_b32_e32 v1, 1, v8
	v_and_b32_e32 v1, 24, v1
	v_and_b32_e32 v0, 15, v8
	v_lshlrev_b32_e32 v2, 1, v1
	v_lshl_or_b32 v202, s4, 6, v0
	v_lshl_or_b32 v0, v0, 6, v2
	v_lshlrev_b32_e32 v2, 2, v8
	v_and_b32_e32 v2, 32, v2
	v_bitop3_b32 v3, v0, s29, v2 bitop3:0xde
	v_bitop3_b32 v203, v0, s35, v2 bitop3:0xde
	v_or_b32_e32 v204, s34, v1
	v_lshrrev_b32_e32 v1, 1, v9
	v_mul_lo_u32 v0, v10, s5
	v_mad_u64_u32 v[0:1], s[34:35], v1, s30, v[0:1]
	v_or_b32_e32 v0, v0, v11
	v_add_lshl_u32 v0, v0, v12, 1
	v_mov_b32_e32 v1, v163
	v_lshl_add_u64 v[168:169], v[0:1], 0, s[6:7]
	v_lshrrev_b32_e32 v1, 1, v13
	v_mul_lo_u32 v0, v14, s5
	v_mad_u64_u32 v[0:1], s[4:5], v1, s30, v[0:1]
	s_waitcnt vmcnt(6)
	s_cmpk_lt_u32 s28, 0x100
	v_or_b32_e32 v0, v0, v15
	s_cselect_b64 s[28:29], -1, 0
	v_add_lshl_u32 v0, v0, v16, 1
	v_mov_b32_e32 v1, v163
	s_add_i32 s69, 0, 0x10000
	s_add_i32 s70, 0, 0x14000
	s_brev_b32 s34, 31
	s_ashr_i32 s66, s48, 31
	s_mov_b32 s67, s48
	s_sub_i32 s2, s2, s99
	s_ashr_i32 s68, s2, 31
	v_lshl_add_u64 v[170:171], v[0:1], 0, s[6:7]
	v_mov_b64_e32 v[172:173], 0x300
	v_mov_b64_e32 v[174:175], 0x2ff
	v_add_u32_e32 v205, s69, v203
	v_add_u32_e32 v208, s70, v203
	v_add_u32_e32 v209, 0, v3
	s_mov_b32 s30, 0x3f9837f0
	s_mov_b32 s35, -1
	v_mov_b64_e32 v[176:177], 0x1ff
	v_mov_b64_e32 v[178:179], 0x200
	s_mov_b32 s71, s19
	s_barrier
	s_branch .LBB0_1184

;     __device__ __forceinline__ const char* a_base(const Unit& u) const { return (const char*)(A + (size_t)u.pm * BM * lda + (agrp ? (u.pn >> 1) * 256 : 0) + u.k0); }
;     __host__ __device__ __forceinline__ bool next(int i, Unit& u) const {
;         const long L = (long)i * G + c; if (L >= nwg + 32 * NSPLIT) return false;
;         Unit a; map(L < nwg ? (int)L : 0, a);
;         const bool sp = L >= nwg; const int j = sp ? (int)L - nwg : 0, tile = j / NSPLIT, ks = j % NSPLIT, base = nch / NSPLIT, rem = nch % NSPLIT;
;         u.pm = sp ? 64 + (tile >> 3) : a.pm; u.pn = sp ? (tile & 7) : a.pn; u.ks = sp ? ks : -1;
;         u.k0 = sp ? (ks * base + (ks < rem ? ks : rem)) * 128 : 0; u.nt = sp ? (base + (ks < rem ? 1 : 0)) * 2 : ntk; return true;
; template <class Epi, class Sched, bool ALIGN_EPI = false, bool SP2 = false>
; __device__ __forceinline__ void gemm_phase(PG8_LAS unsigned char* lds, const Gemm g, const Sched& S, const Epi& E) {
;     ...
;         const bool has_next = S.next(ui + 1, nxt);
;         const char* nA = has_next ? g.a_base(nxt) : cA; const char* nB = has_next ? g.b_base(nxt) : cB;
.LBB0_1184:
	s_add_i32 s71, s71, 1
	s_mul_i32 s4, s71, s66
	s_mul_hi_u32 s5, s71, s67
	s_add_i32 s5, s5, s4
	s_mul_i32 s4, s71, s67
	s_add_u32 s38, s4, s2
	s_addc_u32 s39, s5, s68
	s_cmpk_lt_u32 s38, 0x300
	s_cselect_b32 s98, s99, 0
	s_lshr_b32 s98, s98, 1
	s_sub_u32 s38, s38, s98
	v_cmp_gt_i64_e32 vcc, s[38:39], v[174:175]
	v_cmp_lt_i64_e64 s[6:7], s[38:39], v[172:173]
	s_cbranch_vccnz .LBB0_1193
	s_ashr_i32 s36, s38, 31
	s_lshr_b32 s36, s36, 29
	v_cmp_gt_i64_e64 s[4:5], s[38:39], v[176:177]
	v_cmp_lt_i64_e32 vcc, s[38:39], v[178:179]
	s_add_i32 s39, s38, s36
	s_and_b32 s36, s39, -8
	s_sub_i32 s52, s38, s36
	s_and_b64 s[36:37], vcc, exec
	s_cselect_b32 s53, s52, 0
	s_cmp_gt_i32 s53, -1
	s_mov_b64 s[36:37], -1
	s_cbranch_scc0 .LBB0_1187
	s_lshl_b32 s52, s53, 6
	s_cbranch_execnz .LBB0_1189
	s_branch .LBB0_1188
